# grid barriers after the first two: hipcc's inlined thread-0 bodies replaced by one shared hand-written routine (generation kept in a register, XCD leaders wait on the cross-XCD arrival counter itself:
# speedup vs baseline: 1.0006x; 1.0006x over previous
_Z8fwd_mega4Args:
	s_mov_b32 s98, 2
	s_mov_b32 s99, 0
	s_load_dword s3, s[0:1], 0x108
	s_load_dwordx2 s[30:31], s[0:1], 0x100
	s_load_dwordx8 s[36:43], s[0:1], 0xe0
	s_load_dwordx8 s[8:15], s[0:1], 0xc0
	s_add_u32 s6, s0, 0x100
	v_and_b32_e32 v144, 0x3ff, v0
	s_addc_u32 s7, s1, 0
	s_waitcnt lgkmcnt(0)
	v_writelane_b32 v240, s3, 0
	v_writelane_b32 v240, s8, 1
	v_readfirstlane_b32 s33, v144
	s_nop 0
	v_writelane_b32 v240, s9, 2
	v_writelane_b32 v240, s10, 3
	v_writelane_b32 v240, s11, 4
	v_writelane_b32 v240, s12, 5
	v_writelane_b32 v240, s13, 6
	v_writelane_b32 v240, s14, 7
	v_writelane_b32 v240, s15, 8
	v_cmp_eq_u32_e64 s[8:9], 0, v144
	s_mov_b64 s[4:5], exec
	s_nop 0
	v_writelane_b32 v240, s8, 9
	s_nop 1
	v_writelane_b32 v240, s9, 10
	s_and_b64 s[8:9], s[4:5], s[8:9]
	s_mov_b64 exec, s[8:9]
	s_cbranch_execz .LBB0_2
	s_add_i32 s3, 0, 0x23fc0
	v_mov_b32_e32 v1, 0
	v_mov_b32_e32 v2, s3
	s_add_i32 s3, 0, 0x23fc4
	ds_write_b32 v2, v1
	v_mov_b32_e32 v2, s3
	ds_write_b32 v2, v1

.LBB0_271:
	s_waitcnt vmcnt(0)
	s_waitcnt lgkmcnt(0)
	s_barrier
	s_mov_b64 s[0:1], exec
	v_readlane_b32 s4, v240, 9
	v_readlane_b32 s5, v240, 10
	s_and_b64 s[4:5], s[0:1], s[4:5]
	s_mov_b64 exec, s[4:5]
	s_cbranch_execz .LBB0_323
	s_mov_b32 s99, 2
	s_branch .Lmybar
.Lmybar_ret2:
.LBB0_323:
	s_or_b64 exec, exec, s[0:1]
	s_cmp_lt_i32 s54, 5
	s_cselect_b64 s[0:1], -1, 0
	s_cmp_gt_i32 s55, 4
	s_cselect_b64 s[4:5], -1, 0
	s_and_b64 s[0:1], s[0:1], s[4:5]
	s_andn2_b64 vcc, exec, s[0:1]
	s_waitcnt lgkmcnt(0)
	s_barrier
	s_cbranch_vccnz .LBB0_423
	s_cmpk_lt_i32 s2, 0x540
	s_cselect_b64 s[4:5], -1, 0
	s_cmpk_gt_i32 s2, 0x53f
	v_readfirstlane_b32 s10, v144
	s_cbranch_scc1 .LBB0_326
	s_ashr_i32 s0, s2, 31
	s_lshr_b32 s0, s0, 29
	s_add_i32 s0, s2, s0
	s_ashr_i32 s1, s0, 3
	s_and_b32 s0, s0, -8
	s_sub_i32 s0, s2, s0
	s_cmp_lt_i32 s0, 0
	s_movk_i32 s3, 0xa9
	s_cselect_b32 s3, s3, 0xa8
	s_mul_i32 s0, s0, s3
	s_add_i32 s0, s0, s1
	s_mul_hi_i32 s1, s0, 0x30c30c31
	s_lshr_b32 s3, s1, 31
	s_ashr_i32 s1, s1, 6
	s_add_i32 s1, s1, s3
	s_lshl_b32 s3, s1, 3
	s_mulk_i32 s1, 0x150
	s_sub_i32 s0, s0, s1
	s_sext_i32_i16 s1, s0
	s_bfe_u32 s1, s1, 0x3001c
	s_add_i32 s1, s0, s1
	s_sext_i32_i16 s6, s1
	s_and_b32 s1, s1, 0xfff8
	s_sub_i32 s0, s0, s1
	s_sext_i32_i16 s0, s0
	s_add_i32 s0, s3, s0
	s_ashr_i32 s86, s6, 3

.Lcv_done_p4out:
.LBB0_423:
	s_waitcnt vmcnt(0)
	s_barrier
	s_mov_b64 s[0:1], exec
	v_readlane_b32 s4, v240, 9
	v_readlane_b32 s5, v240, 10
	s_and_b64 s[4:5], s[0:1], s[4:5]
	s_mov_b64 exec, s[4:5]
	s_cbranch_execz .LBB0_475
	s_mov_b32 s99, 3
	s_branch .Lmybar
.Lmybar_ret3:
.LBB0_475:
	s_or_b64 exec, exec, s[0:1]
	s_cmp_lt_i32 s54, 6
	s_cselect_b64 s[0:1], -1, 0
	s_cmp_gt_i32 s55, 5
	s_cselect_b64 s[4:5], -1, 0
	s_and_b64 s[0:1], s[0:1], s[4:5]
	s_andn2_b64 vcc, exec, s[0:1]
	s_waitcnt lgkmcnt(0)
	s_barrier
	s_cbranch_vccnz .LBB0_563
	v_lshlrev_b32_e32 v0, 3, v146
	v_cmp_lt_u32_e32 vcc, 3, v146
	s_mov_b64 s[4:5], 0
	s_mov_b64 s[8:9], -1
	v_mov_b32_e32 v14, 0
	s_mov_b64 s[0:1], 0
	v_mov_b32_e32 v2, 0
	s_and_saveexec_b64 s[6:7], vcc
	s_cbranch_execz .LBB0_486
	v_cmp_lt_u32_e32 vcc, 15, v146
	s_and_saveexec_b64 s[8:9], vcc
	s_xor_b64 s[8:9], exec, s[8:9]
	s_cbranch_execz .LBB0_483
	v_cmp_lt_u32_e32 vcc, 27, v146
	s_and_saveexec_b64 s[4:5], vcc
	s_xor_b64 s[4:5], exec, s[4:5]
	v_add_u32_e32 v1, 0xbc0, v0
	v_cmp_gt_u32_e64 s[0:1], 32, v146
	s_nop 1
	v_cndmask_b32_e64 v2, v1, 0, s[0:1]
	s_or_saveexec_b64 s[10:11], s[4:5]
	s_mov_b64 s[4:5], 0
	s_xor_b64 exec, exec, s[10:11]
	s_mov_b64 s[4:5], exec
	v_add_u32_e32 v2, 0xbe0, v0
	s_andn2_b64 s[0:1], s[0:1], exec
	s_or_b64 exec, exec, s[10:11]

.LBB0_563:
	s_waitcnt vmcnt(0)
	s_barrier
	s_mov_b64 s[0:1], exec
	v_readlane_b32 s4, v240, 9
	v_readlane_b32 s5, v240, 10
	s_and_b64 s[4:5], s[0:1], s[4:5]
	s_mov_b64 exec, s[4:5]
	s_cbranch_execz .LBB0_615
	s_mov_b32 s99, 4
	s_branch .Lmybar
.Lmybar_ret4:
.LBB0_615:
	s_or_b64 exec, exec, s[0:1]
	s_cmp_lt_i32 s54, 7
	s_cselect_b64 s[0:1], -1, 0
	s_cmp_gt_i32 s55, 6
	s_cselect_b64 s[4:5], -1, 0
	s_and_b64 s[0:1], s[0:1], s[4:5]
	s_andn2_b64 vcc, exec, s[0:1]
	s_waitcnt lgkmcnt(0)
	s_barrier
	s_cbranch_vccnz .LBB0_749
	s_cmpk_lt_i32 s2, 0x180
	s_movk_i32 s0, 0x100
	s_cselect_b64 s[4:5], -1, 0
	s_cmpk_gt_i32 s2, 0x17f
	v_readfirstlane_b32 s26, v144
	s_cbranch_scc1 .LBB0_618
	s_ashr_i32 s1, s2, 31
	s_lshr_b32 s1, s1, 29
	s_add_i32 s1, s2, s1
	s_ashr_i32 s3, s1, 3
	s_and_b32 s1, s1, -8
	s_sub_i32 s1, s2, s1
	s_cmp_lt_i32 s1, 0
	s_cselect_b32 s6, 49, 48
	s_mul_i32 s1, s1, s6
	s_add_i32 s1, s1, s3
	s_mul_hi_i32 s3, s1, 0x2aaaaaab
	s_lshr_b32 s6, s3, 31
	s_ashr_i32 s3, s3, 4
	s_add_i32 s3, s3, s6
	s_lshl_b32 s6, s3, 3
	s_mulk_i32 s3, 0x60
	s_sub_i32 s1, s1, s3
	s_bfe_i32 s3, s1, 0x80000
	s_bfe_u32 s3, s3, 0x3000c
	s_add_i32 s3, s1, s3
	s_bfe_i32 s7, s3, 0x80000
	s_and_b32 s3, s3, 0xf8
	s_sub_i32 s1, s1, s3
	s_sext_i32_i16 s7, s7
	s_sext_i32_i8 s1, s1
	s_add_i32 s1, s6, s1
	s_ashr_i32 s88, s7, 3

.LBB0_749:
	s_waitcnt vmcnt(0)
	s_waitcnt lgkmcnt(0)
	s_barrier
	s_mov_b64 s[0:1], exec
	v_readlane_b32 s4, v240, 9
	v_readlane_b32 s5, v240, 10
	s_and_b64 s[4:5], s[0:1], s[4:5]
	s_mov_b64 exec, s[4:5]
	s_cbranch_execz .LBB0_801
	s_mov_b32 s99, 5
	s_branch .Lmybar
.Lmybar_ret5:
.LBB0_801:
	s_or_b64 exec, exec, s[0:1]
	s_cmp_lt_i32 s54, 8
	s_cselect_b64 s[0:1], -1, 0
	s_cmp_gt_i32 s55, 7
	s_cselect_b64 s[4:5], -1, 0
	s_and_b64 s[0:1], s[0:1], s[4:5]
	s_andn2_b64 vcc, exec, s[0:1]
	s_waitcnt lgkmcnt(0)
	s_barrier
	s_cbranch_vccnz .LBB0_1045
	v_lshrrev_b32_e32 v0, 2, v146
	s_ashr_i32 s3, s34, 5
	v_and_b32_e32 v133, 15, v144
	v_and_b32_e32 v100, 12, v0
	s_cmpk_gt_i32 s3, 0xff
	v_or_b32_e32 v147, 3, v0
	v_or_b32_e32 v145, 19, v0
	v_or_b32_e32 v132, 35, v0
	v_or_b32_e32 v101, 51, v0
	s_cbranch_scc1 .LBB0_837
	s_lshl_b32 s0, s34, 6
	s_and_b32 s0, s0, 0x3c0
	v_or_b32_e32 v64, s0, v100
	v_mov_b32_e32 v103, 0
	v_lshlrev_b32_e32 v102, 2, v64
	v_lshl_add_u64 v[24:25], s[40:41], 0, v[102:103]
	s_movk_i32 s28, 0x1000
	v_readlane_b32 s4, v240, 19
	v_add_co_u32_e32 v60, vcc, s28, v24
	v_readlane_b32 s6, v240, 21
	v_readlane_b32 s7, v240, 22
	v_addc_co_u32_e32 v61, vcc, 0, v25, vcc
	global_load_dwordx4 v[0:3], v102, s[40:41]
	global_load_dwordx4 v[4:7], v102, s[40:41] offset:64
	global_load_dwordx4 v[8:11], v102, s[40:41] offset:128
	global_load_dwordx4 v[12:15], v102, s[40:41] offset:192
	v_readlane_b32 s5, v240, 20
	global_load_dwordx4 v[16:19], v102, s[6:7] offset:192
	s_nop 3
	global_load_dwordx4 v[20:23], v102, s[4:5] offset:192
	global_load_dwordx4 v[24:27], v102, s[6:7] offset:128
	global_load_dwordx4 v[28:31], v102, s[4:5] offset:128
	global_load_dwordx4 v[32:35], v[60:61], off offset:192
	global_load_dwordx4 v[36:39], v[60:61], off offset:128
	global_load_dwordx4 v[40:43], v102, s[6:7] offset:64
	global_load_dwordx4 v[44:47], v102, s[4:5] offset:64
	global_load_dwordx4 v[48:51], v102, s[6:7]
	global_load_dwordx4 v[52:55], v102, s[4:5]
	global_load_dwordx4 v[56:59], v[60:61], off offset:64
	s_nop 0
	global_load_dwordx4 v[60:63], v[60:61], off
	v_mbcnt_lo_u32_b32 v65, -1, 0
	v_mbcnt_hi_u32_b32 v65, -1, v65
	v_and_b32_e32 v69, 64, v65
	v_xor_b32_e32 v67, 16, v65
	v_add_u32_e32 v69, 64, v69
	s_mul_i32 s0, s57, 0x1b00
	v_readlane_b32 s10, v240, 25
	v_cmp_lt_i32_e32 vcc, v67, v69
	v_mul_u32_u24_e32 v72, 0x44, v100
	s_add_i32 s20, s0, 0
	v_cndmask_b32_e32 v67, v65, v67, vcc
	s_movk_i32 s10, 0x44
	v_or_b32_e32 v72, v72, v133
	v_lshlrev_b32_e32 v152, 2, v67
	v_xor_b32_e32 v67, 32, v65
	v_lshl_add_u32 v156, v72, 1, s20
	v_mad_u32_u24 v72, v100, s10, s10
	v_cmp_lt_i32_e32 vcc, v67, v69
	v_or_b32_e32 v69, 2, v100
	v_add_u32_e32 v73, v72, v133
	v_lshl_add_u32 v157, v73, 1, s20
	v_mad_u32_u24 v73, v69, s10, v133
	v_lshl_add_u32 v158, v73, 1, s20
	v_mad_u32_u24 v73, v147, s10, v133
	v_cndmask_b32_e32 v65, v65, v67, vcc
	v_lshl_add_u32 v159, v73, 1, s20
	v_or_b32_e32 v73, 16, v133
	v_lshlrev_b32_e32 v153, 2, v65
	v_mad_u32_u24 v65, v133, s10, v100
	v_mad_u32_u24 v74, v100, s10, v73
	v_lshl_add_u32 v155, v65, 1, s20
	v_or_b32_e32 v65, 1, v100
	v_lshl_add_u32 v160, v74, 1, s20
	v_add_u32_e32 v74, v72, v73
	v_cmp_eq_u32_e32 vcc, v65, v133
	v_lshl_add_u32 v161, v74, 1, s20
	v_mad_u32_u24 v74, v69, s10, v73
	v_cndmask_b32_e64 v111, 0, 1.0, vcc
	v_cmp_eq_u32_e32 vcc, v100, v133
	v_lshl_add_u32 v162, v74, 1, s20
	v_mad_u32_u24 v74, v147, s10, v73
	v_cndmask_b32_e64 v110, 0, 1.0, vcc
	v_cmp_eq_u32_e32 vcc, v147, v133
	v_lshl_add_u32 v163, v74, 1, s20
	v_or_b32_e32 v74, 32, v133
	v_cndmask_b32_e64 v113, 0, 1.0, vcc
	v_cmp_eq_u32_e32 vcc, v69, v133
	v_mad_u32_u24 v75, v100, s10, v74
	v_lshl_add_u32 v164, v75, 1, s20
	v_cndmask_b32_e64 v112, 0, 1.0, vcc
	v_add_u32_e32 v75, v72, v74
	v_cmp_eq_u32_e32 vcc, v65, v133
	v_readlane_b32 s12, v240, 27
	v_readlane_b32 s13, v240, 28
	v_readlane_b32 s14, v240, 29
	v_readlane_b32 s15, v240, 30
	s_lshl_b32 s0, s34, 8
	v_or_b32_e32 v67, 48, v133
	v_lshl_add_u32 v165, v75, 1, s20
	v_mad_u32_u24 v75, v69, s10, v74
	v_cndmask_b32_e64 v115, 0, 1.0, vcc
	v_cmp_eq_u32_e32 vcc, v73, v145
	v_readlane_b32 s48, v240, 11
	v_readlane_b32 s11, v240, 26
	s_and_b32 s29, s0, 0x1f00
	s_and_b32 s22, s0, 0x1000
	v_cmp_lt_u32_e64 s[12:13], v133, v69
	v_cmp_lt_u32_e64 s[14:15], v69, v133
	v_lshl_add_u32 v166, v75, 1, s20
	v_mad_u32_u24 v75, v147, s10, v74
	v_add_u32_e32 v72, v72, v67
	v_mad_u32_u24 v69, v69, s10, v67
	v_cndmask_b32_e64 v117, 0, 1.0, vcc
	v_cmp_eq_u32_e32 vcc, v74, v132
	v_readlane_b32 s52, v240, 15
	v_readlane_b32 s53, v240, 16
	v_lshlrev_b32_e32 v102, 1, v64
	v_or_b32_e32 v66, 16, v64
	v_or_b32_e32 v68, 32, v64
	v_or_b32_e32 v70, 48, v64
	v_readlane_b32 s8, v240, 23
	v_readlane_b32 s9, v240, 24
	v_readlane_b32 s16, v240, 31
	v_readlane_b32 s17, v240, 32
	v_readlane_b32 s18, v240, 33
	v_readlane_b32 s19, v240, 34
	v_lshlrev_b32_e32 v106, 4, v146
	v_and_b32_e32 v71, 48, v144
	v_lshl_add_u32 v167, v75, 1, s20
	v_mad_u32_u24 v75, v100, s10, v67
	v_lshl_add_u32 v169, v72, 1, s20
	v_lshl_add_u32 v170, v69, 1, s20
	v_mad_u32_u24 v69, v147, s10, v67
	v_cndmask_b32_e64 v119, 0, 1.0, vcc
	v_cmp_eq_u32_e32 vcc, v67, v101
	v_readlane_b32 s49, v240, 12
	v_readlane_b32 s50, v240, 13
	v_readlane_b32 s51, v240, 14
	s_add_u32 s35, s52, 0x100000
	v_lshl_add_u64 v[72:73], s[52:53], 0, v[102:103]
	s_mov_b64 s[10:11], 0x18800000
	s_mov_b32 s23, 0
	v_cmp_eq_u32_e64 s[0:1], 15, v133
	v_lshl_add_u32 v154, v133, 2, s20
	v_lshlrev_b32_e32 v104, 3, v146
	v_mov_b32_e32 v107, v103
	v_or_b32_e32 v108, 0x400, v106
	v_mov_b32_e32 v109, v103
	v_mov_b32_e32 v105, v103
	v_cmp_lt_u32_e64 s[4:5], v133, v100
	v_cmp_lt_u32_e64 s[6:7], v100, v133
	v_cmp_lt_u32_e64 s[8:9], v65, v133
	v_cmp_lt_u32_e64 s[16:17], v133, v147
	v_cmp_lt_u32_e64 s[18:19], v147, v133
	v_lshl_add_u32 v168, v75, 1, s20
	v_lshl_add_u32 v171, v69, 1, s20
	v_mov_b32_e32 v116, v112
	v_mov_b32_e32 v118, v112
	v_cndmask_b32_e64 v121, 0, 1.0, vcc
	v_mov_b32_e32 v120, v112
	s_addc_u32 s42, s53, 0
	s_ashr_i32 s43, s80, 5
	v_mov_b32_e32 v114, v110
	v_lshl_add_u64 v[122:123], v[72:73], 0, s[10:11]
	s_movk_i32 s46, 0x5400
	s_mov_b64 s[26:27], 0x1800
	s_mov_b64 s[36:37], 0x2000
	v_lshlrev_b32_e32 v102, 1, v64
	s_movk_i32 s47, 0x1800
	s_mov_b32 s48, 0x800000
	s_mov_b32 s49, 0x3f317217
	s_mov_b32 s50, 0x7f800000
	v_lshlrev_b32_e32 v124, 1, v66
	v_lshlrev_b32_e32 v126, 1, v68
	v_lshlrev_b32_e32 v128, 1, v70
	s_mov_b32 s51, 0xf800000
	v_mov_b32_e32 v172, 0x260
	s_mov_b32 s52, 0x5040100
	s_movk_i32 s53, 0x3000
	v_mov_b32_e32 v173, 0x41b17218
	v_add_u32_e32 v174, s20, v71
	v_readlane_b32 s54, v240, 17
	v_readlane_b32 s55, v240, 18
	s_branch .LBB0_805

.LBB0_874:
	s_waitcnt vmcnt(0)
	s_barrier
	s_mov_b64 s[0:1], exec
	v_readlane_b32 s4, v240, 9
	v_readlane_b32 s5, v240, 10
	s_and_b64 s[4:5], s[0:1], s[4:5]
	s_mov_b64 exec, s[4:5]
	s_cbranch_execz .LBB0_926
	s_mov_b32 s99, 6
	s_branch .Lmybar
.Lmybar_ret6:
.LBB0_926:
	s_or_b64 exec, exec, s[0:1]
	s_cmp_lt_i32 s2, 32
	s_cselect_b64 s[0:1], -1, 0
	s_cmp_gt_i32 s2, 31
	s_cselect_b64 s[12:13], -1, 0
	s_cmp_gt_i32 s30, 64
	s_mov_b64 s[4:5], -1
	s_waitcnt lgkmcnt(0)
	s_barrier
	s_cbranch_scc1 .LBB0_990
	s_andn2_b64 vcc, exec, s[0:1]
	s_cbranch_vccnz .LBB0_954
	v_lshlrev_b32_e32 v0, 5, v146
	v_and_b32_e32 v220, 0x600, v0
	v_or_b32_e32 v0, 0x300, v144
	s_movk_i32 s4, 0x31f
	v_and_b32_e32 v3, 0xff, v144
	v_mov_b32_e32 v5, 0xfffffce0
	v_cmp_lt_u32_e32 vcc, s4, v0
	v_mov_b32_e32 v6, 0x3200
	v_or_b32_e32 v8, 0x900, v3
	v_cndmask_b32_e32 v5, 0, v5, vcc
	v_cndmask_b32_e32 v140, 0, v6, vcc
	v_or_b32_e32 v6, 0x600, v3
	v_add_lshl_u32 v142, v5, v0, 4
	v_mul_u32_u24_e32 v0, 0x51f, v6
	v_lshrrev_b32_e32 v7, 20, v0
	v_mul_i32_i24_e32 v0, 0xfffffce0, v7
	v_add_lshl_u32 v154, v0, v6, 4
	v_mul_u32_u24_e32 v0, 0x51f, v8
	v_lshrrev_b32_e32 v9, 20, v0
	v_mul_i32_i24_e32 v0, 0xfffffce0, v9
	v_add_lshl_u32 v162, v0, v8, 4
	v_or_b32_e32 v0, 0xc00, v3
	v_min_u32_e32 v5, 0xc7f, v0
	s_movk_i32 s4, 0x87
	v_lshlrev_b32_e32 v168, 4, v5
	v_mov_b32_e32 v5, 0xffffff78
	v_cmp_lt_u32_e64 s[6:7], s4, v3
	s_movk_i32 s35, 0x5400
	v_or_b32_e32 v1, 0x100, v3
	v_cndmask_b32_e64 v5, 0, v5, s[6:7]
	v_add_u32_e32 v5, v5, v3
	v_lshrrev_b32_e32 v10, 3, v5
	v_cndmask_b32_e64 v11, 0, 16, s[6:7]
	v_add_u32_e32 v10, v10, v11
	v_sub_u32_e64 v11, v10, 1 clamp
	v_mad_u64_u32 v[170:171], s[4:5], v11, s35, 0
	v_lshlrev_b32_e32 v11, 3, v144
	v_and_b32_e32 v132, 56, v11
	v_mul_u32_u24_e32 v11, 0x1e2, v1
	s_movk_i32 s8, 0xff78
	v_lshrrev_b32_e32 v11, 16, v11
	v_mad_i32_i24 v12, v11, s8, v1
	v_ashrrev_i32_e32 v13, 3, v12
	s_waitcnt vmcnt(0)
	v_lshl_add_u32 v14, v11, 4, v13
	v_max_i32_e32 v15, 1, v14
	v_or_b32_e32 v4, 0x200, v3
	v_add_u32_e32 v15, -1, v15
	v_mad_u64_u32 v[172:173], s[4:5], v15, s35, 0
	v_min_u32_e32 v15, 0x21f, v4
	v_lshlrev_b32_e32 v17, 3, v15
	v_and_b32_e32 v176, 56, v17
	v_add_u32_e32 v17, 63, v10
	v_mad_u64_u32 v[178:179], s[4:5], v17, s35, 0
	v_add_u32_e32 v17, 63, v14
	v_mad_u64_u32 v[180:181], s[4:5], v17, s35, 0
	v_mov_b32_e32 v17, 0x3a80
	v_cndmask_b32_e32 v18, 0, v17, vcc
	v_cndmask_b32_e64 v17, 0, v17, s[6:7]
	s_movk_i32 s6, 0x220
	v_readlane_b32 s16, v240, 11
	v_lshlrev_b32_e32 v138, 4, v4
	s_movk_i32 s8, 0x3a80
	v_cmp_gt_u32_e64 s[6:7], s6, v4
	v_add_u32_e32 v4, 0x7f, v10
	s_cmpk_lt_u32 s33, 0x100
	v_readlane_b32 s20, v240, 15
	v_mad_u32_u24 v222, v7, s8, 0
	v_mad_u32_u24 v223, v9, s8, 0
	v_mad_u32_u24 v226, v11, s8, 0
	v_mad_u64_u32 v[182:183], s[8:9], v4, s35, 0
	v_add_u32_e32 v4, 0x7f, v14
	s_cselect_b64 s[14:15], -1, 0
	v_readlane_b32 s21, v240, 16
	s_add_u32 s3, s20, 0x100000
	v_mad_u64_u32 v[184:185], s[8:9], v4, s35, 0
	v_readlane_b32 s17, v240, 12
	s_addc_u32 s28, s21, 0
	v_mov_b32_e32 v2, 0
	v_and_b32_e32 v4, 48, v144
	s_lshr_b32 s8, s33, 1
	s_mov_b32 s17, 0
	v_lshlrev_b32_e32 v225, 4, v5
	v_lshlrev_b32_e32 v4, 9, v4
	v_mov_b32_e32 v5, v2
	s_and_b32 s16, s8, 0x7fffffe0
	s_mov_b32 s8, 0x1e1e1e2
	v_lshlrev_b32_e32 v136, 4, v1
	v_add_u32_e32 v16, 0xfffffe68, v15
	v_lshl_add_u64 v[4:5], v[4:5], 0, s[16:17]
	v_mul_hi_u32 v1, v1, s8
	s_movk_i32 s11, 0xff
	v_lshrrev_b32_e32 v16, 3, v16
	v_lshl_or_b32 v4, v133, 1, v4
	v_lshlrev_b32_e32 v1, 4, v1
	v_mul_u32_u24_e32 v174, 0x5400, v16
	v_lshl_add_u64 v[186:187], s[20:21], 0, v[4:5]
	v_and_b32_e32 v4, 7, v15
	v_add3_u32 v228, v13, v1, s11
	v_add_u32_e32 v1, 0xff, v10
	v_lshl_or_b32 v188, v4, 4, v174
	v_mad_u64_u32 v[4:5], s[8:9], v1, s35, 0
	v_and_b32_e32 v1, 7, v144
	v_readlane_b32 s18, v240, 13
	v_readlane_b32 s19, v240, 14
	v_lshlrev_b32_e32 v13, 4, v1
	v_or_b32_e32 v4, v4, v13
	s_mov_b64 s[18:19], 0xe002800
	v_mov_b32_e32 v1, v2
	s_mov_b64 s[8:9], 0xc7f
	s_movk_i32 s4, 0xc80
	v_lshl_add_u64 v[190:191], v[4:5], 0, s[18:19]
	v_mov_b32_e32 v4, 0xc7f
	v_cmp_gt_u64_e64 s[8:9], s[8:9], v[0:1]
	s_movk_i32 s10, 0xfce0
	v_cmp_gt_u32_e64 s[4:5], s4, v0
	s_mul_i32 s16, s2, 0x320000
	v_cndmask_b32_e64 v0, v4, v0, s[8:9]
	v_lshl_or_b32 v192, v0, 4, s16
	v_mul_hi_u32_u24_e32 v0, 0x51eb86, v8
	v_mad_i32_i24 v4, v9, s10, v3
	v_mov_b32_e32 v5, 0x9000
	s_mul_hi_i32 s11, s2, 0x320000
	v_mul_hi_u32_u24_e32 v1, 0x3200, v0
	v_mul_u32_u24_e32 v0, 0x3200, v0
	v_lshl_add_u32 v4, v4, 4, v5
	v_or_b32_e32 v1, s11, v1
	v_or_b32_e32 v0, s16, v0
	v_ashrrev_i32_e32 v5, 31, v4
	v_lshlrev_b32_e32 v134, 4, v3
	v_lshl_add_u64 v[196:197], v[0:1], 0, v[4:5]
	v_mul_hi_u32_u24_e32 v0, 0x51eb86, v6
	v_mad_i32_i24 v3, v7, s10, v3
	v_mov_b32_e32 v4, 0x6000
	v_mul_hi_u32_u24_e32 v1, 0x3200, v0
	v_mul_u32_u24_e32 v0, 0x3200, v0
	v_lshl_add_u32 v4, v3, 4, v4
	v_or_b32_e32 v1, s11, v1
	v_or_b32_e32 v0, s16, v0
	v_ashrrev_i32_e32 v5, 31, v4
	v_lshl_add_u64 v[198:199], v[0:1], 0, v[4:5]
	v_cndmask_b32_e64 v0, 0, 1, vcc
	v_mul_hi_u32_u24_e32 v1, 0x3200, v0
	v_mul_u32_u24_e32 v0, 0x3200, v0
	v_ashrrev_i32_e32 v143, 31, v142
	v_or_b32_e32 v1, s11, v1
	v_or_b32_e32 v0, s16, v0
	v_lshl_add_u64 v[200:201], v[0:1], 0, v[142:143]
	v_add_u32_e32 v0, 0xbf, v10
	v_add_u32_e32 v224, 0, v17
	v_mov_b32_e32 v193, s11
	v_mov_b32_e32 v195, s11
	v_mad_u64_u32 v[0:1], s[10:11], v0, s35, 0
	s_lshl_b32 s29, s57, 4
	v_lshlrev_b32_e32 v227, 4, v12
	v_add_u32_e32 v11, 0xea00, v224
	v_add_u32_e32 v12, 0xea00, v226
	v_or_b32_e32 v0, v0, v13
	v_or_b32_e32 v145, s29, v133
	v_lshlrev_b32_e32 v147, 4, v146
	v_lshlrev_b32_e32 v177, 3, v146
	v_cmp_gt_u32_e64 s[0:1], 16, v146
	v_mov_b32_e32 v135, v2
	v_mov_b32_e32 v137, v2
	v_mov_b32_e32 v139, v2
	v_mov_b32_e32 v141, v2
	v_add_u32_e32 v148, 0xe00, v134
	v_mov_b32_e32 v149, v2
	v_add_u32_e32 v150, 0x1e00, v134
	v_mov_b32_e32 v151, v2
	v_mul_u32_u24_e32 v152, 0x3200, v7
	v_mov_b32_e32 v153, v2
	v_ashrrev_i32_e32 v155, 31, v154
	v_add_u32_e32 v156, 0xc00, v134
	v_mov_b32_e32 v157, v2
	v_add_u32_e32 v158, 0x1c00, v134
	v_mov_b32_e32 v159, v2
	v_mul_u32_u24_e32 v160, 0x3200, v9
	v_mov_b32_e32 v161, v2
	v_ashrrev_i32_e32 v163, 31, v162
	v_add_u32_e32 v164, 0xa00, v134
	v_mov_b32_e32 v165, v2
	v_add_u32_e32 v166, 0x1a00, v134
	v_mov_b32_e32 v167, v2
	v_mov_b32_e32 v175, v2
	v_add_u32_e32 v221, 0, v18
	v_mov_b32_e32 v169, v2
	s_lshl_b32 s36, s2, 6
	s_lshl_b32 s37, s30, 6
	v_mul_hi_u32_u24_e32 v189, 0x5400, v16
	s_mul_hi_i32 s9, s30, 0x320000
	s_mul_i32 s8, s30, 0x320000
	v_or_b32_e32 v194, s16, v134
	v_lshl_add_u64 v[202:203], v[0:1], 0, s[18:19]
	s_movk_i32 s38, 0x7fff
	s_brev_b32 s39, 16
	s_mov_b32 s42, 0x8001000
	s_mov_b32 s43, 0x8008000
	s_mov_b32 s46, 0x8009000
	s_mov_b32 s47, 0x8010000
	s_mov_b32 s48, 0x8011000
	s_mov_b32 s49, 0x8018000
	s_mov_b32 s50, 0x8019000
	s_mov_b32 s51, 0xf6000
	s_mov_b32 s52, 0xc000
	s_mov_b32 s53, 0x246000
	s_mov_b64 s[18:19], 0x19000
	s_mov_b32 s54, 0x19000
	s_mov_b32 s55, 0x396000
	v_add_u32_e32 v229, v11, v225
	v_add_u32_e32 v230, v12, v227
	s_mov_b32 s58, 0x125000
	s_mov_b32 s59, 0x132000
	s_mov_b64 s[20:21], 0x2a0000
	s_mov_b32 s60, s2
	v_readlane_b32 s22, v240, 17
	v_readlane_b32 s23, v240, 18
	s_branch .LBB0_930

.LBB0_1045:
	s_waitcnt vmcnt(0)
	s_waitcnt lgkmcnt(0)
	s_barrier
	s_mov_b64 s[0:1], exec
	v_readlane_b32 s4, v240, 9
	v_readlane_b32 s5, v240, 10
	s_and_b64 s[4:5], s[0:1], s[4:5]
	s_mov_b64 exec, s[4:5]
	s_cbranch_execz .LBB0_1097
	s_mov_b32 s99, 7
	s_branch .Lmybar
.Lmybar_ret7:
.LBB0_1097:
	s_or_b64 exec, exec, s[0:1]
	s_cmp_lt_i32 s54, 9
	s_cselect_b64 s[0:1], -1, 0
	s_cmp_gt_i32 s55, 8
	s_cselect_b64 s[4:5], -1, 0
	s_and_b64 s[0:1], s[0:1], s[4:5]
	s_andn2_b64 vcc, exec, s[0:1]
	s_waitcnt lgkmcnt(0)
	s_barrier
	s_cbranch_vccnz .LBB0_1102
	s_waitcnt vmcnt(15)
	v_lshrrev_b32_e32 v0, 3, v146
	s_ashr_i32 s0, s34, 1
	s_waitcnt vmcnt(4)
	v_and_or_b32 v56, s0, -8, v0
	s_movk_i32 s3, 0x2000
	v_cmp_gt_i32_e32 vcc, s3, v56
	s_and_saveexec_b64 s[6:7], vcc
	s_cbranch_execz .LBB0_1101
	s_lshl_b32 s0, s34, 6
	s_and_b32 s0, s0, 0x3c0
	v_lshlrev_b32_e32 v0, 3, v144
	s_waitcnt vmcnt(0)
	v_and_or_b32 v68, v0, 56, s0
	v_mov_b32_e32 v59, 0
	v_lshlrev_b32_e32 v58, 2, v68
	v_lshl_add_u64 v[32:33], s[40:41], 0, v[58:59]
	v_readlane_b32 s8, v240, 19
	v_add_co_u32_e32 v34, vcc, s3, v32
	v_readlane_b32 s14, v240, 25
	v_readlane_b32 s15, v240, 26
	v_readlane_b32 s16, v240, 27
	v_readlane_b32 s17, v240, 28
	v_addc_co_u32_e32 v35, vcc, 0, v33, vcc
	s_nop 3
	global_load_dwordx4 v[0:3], v58, s[16:17]
	global_load_dwordx4 v[4:7], v58, s[40:41] offset:16
	global_load_dwordx4 v[8:11], v58, s[40:41]
	global_load_dwordx4 v[12:15], v58, s[14:15]
	global_load_dwordx4 v[16:19], v58, s[16:17] offset:16
	global_load_dwordx4 v[20:23], v58, s[14:15] offset:16
	global_load_dwordx4 v[24:27], v[34:35], off offset:-4096
	global_load_dwordx4 v[28:31], v[34:35], off
	s_mov_b64 s[0:1], 0x1000
	v_lshl_add_u64 v[60:61], v[32:33], 0, s[0:1]
	s_mov_b64 s[0:1], 0x2000
	v_readlane_b32 s10, v240, 21
	v_readlane_b32 s11, v240, 22
	v_readlane_b32 s12, v240, 23
	v_readlane_b32 s13, v240, 24
	v_lshl_add_u64 v[62:63], v[32:33], 0, s[0:1]
	global_load_dwordx4 v[32:35], v[60:61], off offset:16
	global_load_dwordx4 v[36:39], v[62:63], off offset:16
	global_load_dwordx4 v[40:43], v58, s[10:11] offset:16
	s_nop 0
	global_load_dwordx4 v[44:47], v58, s[12:13] offset:16
	global_load_dwordx4 v[48:51], v58, s[10:11]
	global_load_dwordx4 v[52:55], v58, s[12:13]
	s_ashr_i32 s0, s80, 1
	v_ashrrev_i32_e32 v57, 31, v56
	s_and_b32 s12, s0, -8
	v_readlane_b32 s9, v240, 20
	v_readlane_b32 s18, v240, 29
	v_readlane_b32 s19, v240, 30
	v_readlane_b32 s20, v240, 31
	v_readlane_b32 s21, v240, 32
	v_readlane_b32 s22, v240, 33
	v_readlane_b32 s23, v240, 34
	s_movk_i32 s1, 0x1800
	v_mov_b64_e32 v[64:65], s[52:53]
	s_movk_i32 s11, 0x5400
	v_lshlrev_b64 v[66:67], 11, v[56:57]
	s_ashr_i32 s13, s12, 31
	s_movk_i32 s10, 0x1000
	s_mov_b64 s[8:9], 0
	s_mov_b32 s20, 0xe001000
	s_mov_b32 s21, 0xe002000
	s_mov_b32 s22, 0x18800000
	s_mov_b32 s23, 0x18801000
	s_brev_b32 s26, 16
	s_mov_b32 s27, 0xffff0000
	v_mov_b32_e32 v76, 0x3a27c5ac
	s_mov_b32 s28, 0x800000
	s_movk_i32 s29, 0x7fff
	v_mov_b32_e32 v61, v59
	v_mad_i64_i32 v[62:63], s[0:1], v56, s1, v[64:65]
	v_mad_i64_i32 v[64:65], s[0:1], v56, s11, v[64:65]
	v_lshl_add_u64 v[66:67], s[52:53], 0, v[66:67]
	s_mul_hi_i32 s15, s12, 0x1800
	s_mul_i32 s14, s12, 0x1800
	s_mul_hi_i32 s17, s12, 0x5400
	s_mul_i32 s16, s12, 0x5400
	v_lshlrev_b32_e32 v60, 1, v68
	s_lshl_b64 s[18:19], s[12:13], 11
	v_lshlrev_b32_e32 v58, 1, v68
	s_movk_i32 s33, 0x1fff
	s_waitcnt vmcnt(13)
	v_mov_b32_e32 v68, v1
	v_mov_b32_e32 v69, v3
	v_mov_b32_e32 v1, v2
	s_waitcnt vmcnt(10)
	v_mov_b32_e32 v70, v13
	v_mov_b32_e32 v71, v15
	v_mov_b32_e32 v13, v14
	s_waitcnt vmcnt(9)
	v_mov_b32_e32 v2, v17
	v_mov_b32_e32 v3, v19
	s_waitcnt vmcnt(8)
	v_mov_b32_e32 v14, v21
	v_mov_b32_e32 v15, v23
	v_mov_b32_e32 v17, v18
	v_mov_b32_e32 v21, v22
	s_waitcnt vmcnt(6)
	v_mov_b32_e32 v18, v29
	v_mov_b32_e32 v19, v31
	v_mov_b32_e32 v29, v30
	s_waitcnt vmcnt(4)
	v_mov_b32_e32 v22, v37
	v_mov_b32_e32 v23, v39
	v_mov_b32_e32 v37, v38

.LBB0_1102:
	s_waitcnt vmcnt(0)
	s_barrier
	s_mov_b64 s[0:1], exec
	v_readlane_b32 s4, v240, 9
	v_readlane_b32 s5, v240, 10
	s_and_b64 s[4:5], s[0:1], s[4:5]
	s_mov_b64 exec, s[4:5]
	s_cbranch_execz .LBB0_1154
	s_mov_b32 s99, 8
	s_branch .Lmybar
.Lmybar_ret8:
.LBB0_1154:
	s_or_b64 exec, exec, s[0:1]
	s_cmp_lt_i32 s54, 10
	s_cselect_b64 s[0:1], -1, 0
	s_cmp_gt_i32 s55, 9
	s_cselect_b64 s[4:5], -1, 0
	s_and_b64 s[0:1], s[0:1], s[4:5]
	s_andn2_b64 vcc, exec, s[0:1]
	s_waitcnt lgkmcnt(0)
	s_barrier
	s_cbranch_vccnz .LBB0_1179
	s_cmpk_gt_i32 s2, 0xff
	v_readfirstlane_b32 s10, v144
	s_cbranch_scc1 .LBB0_1179
	s_ashr_i32 s3, s2, 31
	s_lshr_b32 s0, s3, 29
	s_add_i32 s5, s2, s0
	s_and_b32 s0, s5, -8
	s_sub_i32 s6, s2, s0
	s_cmp_gt_i32 s6, -1
	s_cbranch_scc0 .LBB0_1158
	s_lshl_b32 s4, s6, 5
	s_cbranch_execz .LBB0_1159
	s_branch .LBB0_1160

.LBB0_1179:
	s_waitcnt vmcnt(0)
	s_barrier
	s_mov_b64 s[0:1], exec
	v_readlane_b32 s4, v240, 9
	v_readlane_b32 s5, v240, 10
	s_and_b64 s[4:5], s[0:1], s[4:5]
	s_mov_b64 exec, s[4:5]
	s_cbranch_execz .LBB0_1231
	s_mov_b32 s99, 9
	s_branch .Lmybar
.Lmybar_ret9:
.LBB0_1231:
	s_or_b64 exec, exec, s[0:1]
	s_cmp_lt_i32 s54, 11
	s_cselect_b64 s[0:1], -1, 0
	s_cmp_gt_i32 s55, 10
	s_cselect_b64 s[4:5], -1, 0
	s_and_b64 s[0:1], s[0:1], s[4:5]
	s_andn2_b64 vcc, exec, s[0:1]
	s_waitcnt lgkmcnt(0)
	s_barrier
	s_cbranch_vccnz .LBB0_1276
	s_cmpk_lt_i32 s2, 0x100
	s_cselect_b64 s[0:1], -1, 0
	s_cmpk_gt_i32 s2, 0xff
	v_readfirstlane_b32 s6, v144
	s_cbranch_scc1 .LBB0_1238
	s_ashr_i32 s3, s2, 31
	s_lshr_b32 s3, s3, 29
	s_add_i32 s3, s2, s3
	s_and_b32 s4, s3, -8
	s_sub_i32 s7, s2, s4
	s_cmp_gt_i32 s7, -1
	s_cbranch_scc0 .LBB0_1235
	s_lshl_b32 s8, s7, 5
	s_cbranch_execz .LBB0_1236
	s_branch .LBB0_1237

.LBB0_1276:
	s_waitcnt vmcnt(0)
	s_waitcnt lgkmcnt(0)
	s_barrier
	s_mov_b64 s[0:1], exec
	v_readlane_b32 s4, v240, 9
	v_readlane_b32 s5, v240, 10
	s_and_b64 s[4:5], s[0:1], s[4:5]
	s_mov_b64 exec, s[4:5]
	s_cbranch_execz .LBB0_1328
	s_mov_b32 s99, 10
	s_branch .Lmybar
.Lmybar_ret10:
.LBB0_1328:
	s_or_b64 exec, exec, s[0:1]
	s_cmp_lt_i32 s54, 13
	s_cselect_b64 s[0:1], -1, 0
	s_cmp_gt_i32 s55, 12
	s_cselect_b64 s[4:5], -1, 0
	s_and_b64 s[0:1], s[0:1], s[4:5]
	s_andn2_b64 vcc, exec, s[0:1]
	s_waitcnt lgkmcnt(0)
	s_barrier
	s_cbranch_vccnz .LBB0_1356
	s_cmpk_gt_i32 s2, 0x57f
	v_readfirstlane_b32 s1, v144
	s_cbranch_scc1 .LBB0_1345
	s_waitcnt vmcnt(15)
	v_lshrrev_b32_e32 v0, 5, v144
	v_lshrrev_b32_e32 v2, 1, v144
	v_and_b32_e32 v0, 4, v0
	v_bfe_u32 v1, v144, 2, 2
	s_waitcnt vmcnt(14)
	v_and_b32_e32 v11, 24, v2
	v_or3_b32 v0, v0, v1, v11
	v_lshlrev_b32_e32 v1, 4, v144
	v_add_u32_e32 v8, 0x2000, v1
	v_lshrrev_b32_e32 v2, 7, v8
	s_movk_i32 s0, 0xe0
	s_waitcnt vmcnt(13)
	v_and_b32_e32 v4, 32, v144
	v_and_or_b32 v3, v2, s0, v0
	v_bitop3_b32 v9, v1, v4, 48 bitop3:0x6c
	v_and_b32_e32 v10, 64, v144
	s_waitcnt vmcnt(12)
	v_bfe_u32 v12, v144, 2, 4
	s_movk_i32 s0, 0xf0
	v_or_b32_e32 v1, v9, v10
	v_and_or_b32 v2, v2, s0, v12
	s_waitcnt vmcnt(0)
	v_lshl_or_b32 v130, v2, 12, v1
	v_lshrrev_b32_e32 v2, 3, v144
	s_movk_i32 s0, 0x60
	v_and_or_b32 v0, v2, s0, v0
	s_movk_i32 s0, 0x70
	s_ashr_i32 s28, s2, 31
	v_lshl_or_b32 v132, v0, 12, v1
	v_and_or_b32 v0, v2, s0, v12
	s_lshr_b32 s0, s28, 29
	s_add_i32 s0, s2, s0
	s_lshr_b32 s11, s1, 6
	s_ashr_i32 s4, s0, 3
	s_and_b32 s0, s0, -8
	s_lshr_b32 s10, s1, 8
	s_lshl_b32 s3, s11, 10
	s_sub_i32 s0, s2, s0
	s_cmp_lt_i32 s0, 0
	s_movk_i32 s29, 0xb1
	s_cselect_b32 s5, s29, 0xb0
	s_mul_i32 s0, s0, s5
	s_add_i32 s0, s0, s4
	s_mul_hi_i32 s4, s0, 0x2e8ba2e9
	s_lshr_b32 s5, s4, 31
	s_ashr_i32 s4, s4, 6
	s_add_i32 s4, s4, s5
	s_lshl_b32 s5, s4, 3
	s_mulk_i32 s4, 0x160
	s_sub_i32 s4, s0, s4
	s_sext_i32_i16 s0, s4
	s_bfe_u32 s0, s0, 0x3001c
	s_add_i32 s6, s4, s0
	s_sext_i32_i16 s0, s6
	s_and_b32 s6, s6, 0xfff8
	s_sub_i32 s4, s4, s6
	s_sext_i32_i16 s4, s4
	s_lshr_b32 s0, s0, 3
	s_add_i32 s4, s5, s4
	s_ashr_i32 s5, s4, 31
	s_bfe_i64 s[8:9], s[0:1], 0x100000
	s_lshl_b64 s[6:7], s[4:5], 20
	s_lshl_b64 s[8:9], s[8:9], 20
	s_add_u32 s36, s50, s8
	s_addc_u32 s37, s51, s9
	s_add_i32 s33, s3, 0
	s_add_i32 m0, s33, 0x10000
	v_lshl_or_b32 v128, v3, 12, v1
	global_load_lds_dwordx4 v132, s[36:37]
	s_add_i32 m0, s33, 0x12000
	s_add_u32 s8, s36, 0x80000
	global_load_lds_dwordx4 v128, s[36:37]
	s_addc_u32 s9, s37, 0
	s_add_i32 m0, s33, 0x14000
	v_lshl_or_b32 v134, v0, 12, v1
	global_load_lds_dwordx4 v132, s[8:9]
	s_add_i32 m0, s33, 0x16000
	s_add_u32 s26, s82, s6
	s_addc_u32 s27, s83, s7
	s_add_i32 s35, s33, 0x2000
	global_load_lds_dwordx4 v128, s[8:9]
	s_mov_b32 m0, s33
	s_add_u32 s6, s26, 0x80000
	global_load_lds_dwordx4 v134, s[26:27]
	s_mov_b32 m0, s35
	s_addc_u32 s7, s27, 0
	s_add_i32 s40, s33, 0x4000
	global_load_lds_dwordx4 v130, s[26:27]
	s_mov_b32 m0, s40
	s_add_i32 s41, s33, 0x6000
	global_load_lds_dwordx4 v134, s[6:7]
	s_mov_b32 m0, s41
	v_mov_b32_e32 v133, 0
	global_load_lds_dwordx4 v130, s[6:7]
	v_mov_b32_e32 v129, v133
	v_mov_b32_e32 v135, v133
	v_mov_b32_e32 v131, v133
	s_cmp_eq_u32 s10, 1
	s_mov_b32 s42, 0
	v_lshl_add_u64 v[6:7], s[36:37], 0, v[132:133]
	v_lshl_add_u64 v[4:5], s[36:37], 0, v[128:129]
	v_lshl_add_u64 v[0:1], s[26:27], 0, v[134:135]
	s_cselect_b64 s[6:7], -1, 0
	s_cmp_lg_u32 s10, 1
	v_lshl_add_u64 v[2:3], s[26:27], 0, v[130:131]
	s_cbranch_scc1 .LBB0_1332
	s_barrier

.Lcv_done_p12dn:
.LBB0_1356:
	s_waitcnt vmcnt(0)
	s_barrier
	s_mov_b64 s[0:1], exec
	v_readlane_b32 s4, v240, 9
	v_readlane_b32 s5, v240, 10
	s_and_b64 s[4:5], s[0:1], s[4:5]
	s_mov_b64 exec, s[4:5]
	s_cbranch_execz .LBB0_1408
	s_mov_b32 s99, 11
	s_branch .Lmybar
.Lmybar_ret11:
.LBB0_1408:
	s_or_b64 exec, exec, s[0:1]
	s_cmpk_lg_i32 s30, 0x100
	s_mov_b64 s[0:1], -1
	s_waitcnt lgkmcnt(0)
	s_barrier
	s_cbranch_scc0 .LBB0_1513
	s_cmp_lt_i32 s54, 14
	s_cselect_b64 s[0:1], -1, 0
	s_cmp_gt_i32 s55, 13
	s_cselect_b64 s[4:5], -1, 0
	s_and_b64 s[0:1], s[0:1], s[4:5]
	s_andn2_b64 vcc, exec, s[0:1]
	s_cbranch_vccnz .LBB0_1456
	s_cmpk_lt_i32 s2, 0x100
	s_cselect_b64 s[0:1], -1, 0
	s_cmpk_gt_i32 s2, 0xff
	v_readfirstlane_b32 s6, v144
	s_cbranch_scc1 .LBB0_1416
	s_ashr_i32 s3, s2, 31
	s_lshr_b32 s3, s3, 29
	s_add_i32 s8, s2, s3
	s_and_b32 s3, s8, -8
	s_sub_i32 s3, s2, s3
	s_cmp_gt_i32 s3, -1
	s_cbranch_scc0 .LBB0_1413
	s_lshl_b32 s7, s3, 5
	s_ashr_i32 s4, s8, 3
	s_cbranch_execz .LBB0_1414
	s_branch .LBB0_1415

.Lmybar:
	v_readlane_b32 s100, v240, 35
	v_readlane_b32 s101, v240, 36
	v_mov_b32_e32 v247, 0x23fc0
	ds_read2_b32 v[248:249], v247 offset1:1
	v_mov_b32_e32 v250, s56
	v_lshlrev_b32_e32 v250, 8, v250
	v_add_u32_e32 v250, 0x1400, v250
	v_mov_b32_e32 v251, 1
	s_add_u32 s98, s98, 1
	s_waitcnt vmcnt(0)
	s_nop 1
	global_atomic_add v252, v250, v251, s[100:101] sc0
	s_waitcnt vmcnt(0) lgkmcnt(0)
	v_mul_lo_u32 v253, v248, s98
	v_add_u32_e32 v252, 1, v252
	v_add_u32_e32 v254, 0x1000, v250
	v_cmp_eq_u32_e32 vcc, v252, v253
	s_cbranch_vccz .Lmb_local
	buffer_wbl2 sc1
	s_waitcnt vmcnt(0)
	v_mov_b32_e32 v250, 0x3400
	global_atomic_add v250, v251, s[100:101]
	v_mul_lo_u32 v253, v249, s98
	v_mov_b32_e32 v255, 0
.Lmb_spin_top:
	global_load_dword v252, v250, s[100:101] sc1
	s_waitcnt vmcnt(0)
	v_cmp_lt_u32_e32 vcc, v252, v253
	s_cbranch_vccz .Lmb_top_ok
	s_sleep 1
	v_add_u32_e32 v255, 1, v255
	v_cmp_gt_u32_e32 vcc, 0x4000, v255
	s_cbranch_vccnz .Lmb_spin_top
.Lmb_top_ok:
	buffer_inv sc1
	global_atomic_add v254, v251, s[100:101]
	s_waitcnt vmcnt(0)
	s_branch .Lmb_done
.Lmb_local:
	v_mov_b32_e32 v255, 0
	v_mov_b32_e32 v253, s98
.Lmb_spin_loc:
	global_load_dword v252, v254, s[100:101] sc1
	s_waitcnt vmcnt(0)
	v_cmp_lt_u32_e32 vcc, v252, v253
	s_cbranch_vccz .Lmb_loc_ok
	s_sleep 1
	v_add_u32_e32 v255, 1, v255
	v_cmp_gt_u32_e32 vcc, 0x4000, v255
	s_cbranch_vccnz .Lmb_spin_loc

.Lmb_done:
	s_cmp_eq_u32 s99, 2
	s_cbranch_scc1 .Lmybar_ret2
	s_cmp_eq_u32 s99, 3
	s_cbranch_scc1 .Lmybar_ret3
	s_cmp_eq_u32 s99, 4
	s_cbranch_scc1 .Lmybar_ret4
	s_cmp_eq_u32 s99, 5
	s_cbranch_scc1 .Lmybar_ret5
	s_cmp_eq_u32 s99, 6
	s_cbranch_scc1 .Lmybar_ret6
	s_cmp_eq_u32 s99, 7
	s_cbranch_scc1 .Lmybar_ret7
	s_cmp_eq_u32 s99, 8
	s_cbranch_scc1 .Lmybar_ret8
	s_cmp_eq_u32 s99, 9
	s_cbranch_scc1 .Lmybar_ret9
	s_cmp_eq_u32 s99, 10
	s_cbranch_scc1 .Lmybar_ret10
	s_cmp_eq_u32 s99, 11
	s_cbranch_scc1 .Lmybar_ret11
	s_branch .Lmybar_ret12

.LBB0_1559:
	s_or_b64 exec, exec, s[2:3]
	s_waitcnt vmcnt(0)
	s_waitcnt lgkmcnt(0)
	s_barrier
	s_mov_b64 s[2:3], exec
	v_readlane_b32 s4, v240, 9
	v_readlane_b32 s5, v240, 10
	s_and_b64 s[4:5], s[2:3], s[4:5]
	s_xor_b64 s[2:3], s[4:5], s[2:3]
	s_mov_b64 exec, s[4:5]
	s_cbranch_execz .LBB0_1612
	s_mov_b32 s99, 12
	s_branch .Lmybar
.Lmybar_ret12:
.LBB0_1612:
	s_or_b64 exec, exec, s[2:3]
	v_lshlrev_b64 v[130:131], 2, v[130:131]
	v_lshl_add_u64 v[8:9], s[48:49], 0, v[130:131]
	v_lshlrev_b64 v[164:165], 11, v[156:157]
	v_lshlrev_b64 v[156:157], 11, v[160:161]
	s_waitcnt lgkmcnt(0)
	s_barrier
	global_load_dwordx4 v[4:7], v[8:9], off offset:16
	global_load_dwordx4 v[12:15], v[8:9], off
	global_load_dwordx4 v[0:3], v[8:9], off offset:528
	s_nop 0
	global_load_dwordx4 v[8:11], v[8:9], off offset:512
	s_nop 0
	global_load_dword v161, v[112:113], off sc1
	v_mov_b32_e32 v160, 0x358637bd
	s_mov_b32 s2, 0x800000
	v_lshlrev_b64 v[172:173], 11, v[134:135]
	v_lshlrev_b64 v[134:135], 11, v[162:163]
	v_lshlrev_b64 v[170:171], 11, v[132:133]
	v_lshl_add_u64 v[132:133], v[132:133], 2, s[0:1]
	v_lshlrev_b64 v[168:169], 11, v[136:137]
	v_lshlrev_b64 v[166:167], 11, v[138:139]
	v_lshlrev_b64 v[158:159], 11, v[158:159]
	s_waitcnt vmcnt(0)
	v_fmamk_f32 v161, v161, 0x3a000000, v160
	v_mul_f32_e32 v162, 0x4b800000, v161
	v_cmp_gt_f32_e32 vcc, s2, v161
	s_nop 1
	v_cndmask_b32_e32 v161, v161, v162, vcc
	v_rsq_f32_e32 v161, v161
	v_lshl_add_u64 v[162:163], v[172:173], 2, s[50:51]
	v_lshl_add_u64 v[162:163], v[162:163], 0, v[130:131]
	v_mul_f32_e32 v172, 0x45800000, v161
	v_cndmask_b32_e32 v172, v161, v172, vcc
	v_pk_mul_f32 v[124:125], v[124:125], v[172:173] op_sel_hi:[1,0]
	v_pk_mul_f32 v[126:127], v[126:127], v[172:173] op_sel_hi:[1,0]
	v_pk_mul_f32 v[174:175], v[120:121], v[172:173] op_sel_hi:[1,0]
	v_pk_mul_f32 v[120:121], v[122:123], v[172:173] op_sel_hi:[1,0]
	v_pk_mul_f32 v[122:123], v[116:117], v[172:173] op_sel_hi:[1,0]
	v_pk_mul_f32 v[176:177], v[118:119], v[172:173] op_sel_hi:[1,0]
	v_pk_mul_f32 v[178:179], v[128:129], v[172:173] op_sel_hi:[1,0]
	v_pk_mul_f32 v[128:129], v[114:115], v[172:173] op_sel_hi:[1,0]
	v_pk_mul_f32 v[116:117], v[14:15], v[126:127]
	v_pk_mul_f32 v[114:115], v[12:13], v[124:125]
	v_pk_mul_f32 v[120:121], v[6:7], v[120:121]
	v_pk_mul_f32 v[118:119], v[4:5], v[174:175]
	v_pk_mul_f32 v[124:125], v[10:11], v[176:177]
	v_pk_mul_f32 v[122:123], v[8:9], v[122:123]
	v_pk_mul_f32 v[128:129], v[2:3], v[128:129]
	v_pk_mul_f32 v[126:127], v[0:1], v[178:179]
	global_store_dwordx4 v[162:163], v[114:117], off
	global_store_dwordx4 v[162:163], v[118:121], off offset:16
	global_store_dwordx4 v[162:163], v[122:125], off offset:512
	global_store_dwordx4 v[162:163], v[126:129], off offset:528
	global_load_dword v114, v[132:133], off sc1
	v_lshl_add_u64 v[116:117], v[136:137], 2, s[0:1]
	s_waitcnt vmcnt(0)
	v_fmamk_f32 v114, v114, 0x3a000000, v160
	v_mul_f32_e32 v115, 0x4b800000, v114
	v_cmp_gt_f32_e32 vcc, s2, v114
	s_nop 1
	v_cndmask_b32_e32 v114, v114, v115, vcc
	v_rsq_f32_e32 v118, v114
	v_lshl_add_u64 v[114:115], v[170:171], 2, s[50:51]
	v_lshl_add_u64 v[114:115], v[114:115], 0, v[130:131]
	v_mul_f32_e32 v119, 0x45800000, v118
	v_cndmask_b32_e32 v118, v118, v119, vcc
	v_pk_mul_f32 v[108:109], v[108:109], v[118:119] op_sel_hi:[1,0]
	v_pk_mul_f32 v[110:111], v[110:111], v[118:119] op_sel_hi:[1,0]
	v_pk_mul_f32 v[104:105], v[104:105], v[118:119] op_sel_hi:[1,0]
	v_pk_mul_f32 v[106:107], v[106:107], v[118:119] op_sel_hi:[1,0]
	v_pk_mul_f32 v[120:121], v[100:101], v[118:119] op_sel_hi:[1,0]
	v_pk_mul_f32 v[122:123], v[102:103], v[118:119] op_sel_hi:[1,0]
	v_pk_mul_f32 v[124:125], v[96:97], v[118:119] op_sel_hi:[1,0]
	v_pk_mul_f32 v[118:119], v[98:99], v[118:119] op_sel_hi:[1,0]
	v_pk_mul_f32 v[98:99], v[14:15], v[110:111]
	v_pk_mul_f32 v[96:97], v[12:13], v[108:109]
	v_pk_mul_f32 v[102:103], v[6:7], v[106:107]
	v_pk_mul_f32 v[100:101], v[4:5], v[104:105]
	v_pk_mul_f32 v[106:107], v[10:11], v[122:123]
	v_pk_mul_f32 v[104:105], v[8:9], v[120:121]
	v_pk_mul_f32 v[110:111], v[2:3], v[118:119]
	v_pk_mul_f32 v[108:109], v[0:1], v[124:125]
	global_store_dwordx4 v[114:115], v[96:99], off
	global_store_dwordx4 v[114:115], v[100:103], off offset:16
	global_store_dwordx4 v[114:115], v[104:107], off offset:512
	global_store_dwordx4 v[114:115], v[108:111], off offset:528
	global_load_dword v96, v[116:117], off sc1
	v_lshl_add_u64 v[98:99], v[138:139], 2, s[0:1]
	s_waitcnt vmcnt(0)
	v_fmamk_f32 v96, v96, 0x3a000000, v160
	v_mul_f32_e32 v97, 0x4b800000, v96
	v_cmp_gt_f32_e32 vcc, s2, v96
	s_nop 1
	v_cndmask_b32_e32 v96, v96, v97, vcc
	v_rsq_f32_e32 v100, v96
	v_lshl_add_u64 v[96:97], v[168:169], 2, s[50:51]
	v_lshl_add_u64 v[96:97], v[96:97], 0, v[130:131]
	v_mul_f32_e32 v101, 0x45800000, v100
	v_cndmask_b32_e32 v100, v100, v101, vcc
	v_pk_mul_f32 v[92:93], v[92:93], v[100:101] op_sel_hi:[1,0]
	v_pk_mul_f32 v[94:95], v[94:95], v[100:101] op_sel_hi:[1,0]
	v_pk_mul_f32 v[88:89], v[88:89], v[100:101] op_sel_hi:[1,0]
	v_pk_mul_f32 v[90:91], v[90:91], v[100:101] op_sel_hi:[1,0]
	v_pk_mul_f32 v[102:103], v[84:85], v[100:101] op_sel_hi:[1,0]
	v_pk_mul_f32 v[104:105], v[86:87], v[100:101] op_sel_hi:[1,0]
	v_pk_mul_f32 v[106:107], v[80:81], v[100:101] op_sel_hi:[1,0]
	v_pk_mul_f32 v[100:101], v[82:83], v[100:101] op_sel_hi:[1,0]
	v_pk_mul_f32 v[82:83], v[14:15], v[94:95]
	v_pk_mul_f32 v[80:81], v[12:13], v[92:93]
	v_pk_mul_f32 v[86:87], v[6:7], v[90:91]
	v_pk_mul_f32 v[84:85], v[4:5], v[88:89]
	v_pk_mul_f32 v[90:91], v[10:11], v[104:105]
	v_pk_mul_f32 v[88:89], v[8:9], v[102:103]
	v_pk_mul_f32 v[94:95], v[2:3], v[100:101]
	v_pk_mul_f32 v[92:93], v[0:1], v[106:107]
	global_store_dwordx4 v[96:97], v[80:83], off
	global_store_dwordx4 v[96:97], v[84:87], off offset:16
	global_store_dwordx4 v[96:97], v[88:91], off offset:512
	global_store_dwordx4 v[96:97], v[92:95], off offset:528
	global_load_dword v80, v[98:99], off sc1
	s_waitcnt vmcnt(0)
	v_fmamk_f32 v80, v80, 0x3a000000, v160
	v_mul_f32_e32 v81, 0x4b800000, v80
	v_cmp_gt_f32_e32 vcc, s2, v80
	s_nop 1
	v_cndmask_b32_e32 v80, v80, v81, vcc
	v_rsq_f32_e32 v82, v80
	v_lshl_add_u64 v[80:81], v[166:167], 2, s[50:51]
	v_lshl_add_u64 v[80:81], v[80:81], 0, v[130:131]
	v_mul_f32_e32 v83, 0x45800000, v82
	v_cndmask_b32_e32 v82, v82, v83, vcc
	v_pk_mul_f32 v[76:77], v[76:77], v[82:83] op_sel_hi:[1,0]
	v_pk_mul_f32 v[78:79], v[78:79], v[82:83] op_sel_hi:[1,0]
	v_pk_mul_f32 v[72:73], v[72:73], v[82:83] op_sel_hi:[1,0]
	v_pk_mul_f32 v[74:75], v[74:75], v[82:83] op_sel_hi:[1,0]
	v_pk_mul_f32 v[84:85], v[68:69], v[82:83] op_sel_hi:[1,0]
	v_pk_mul_f32 v[86:87], v[70:71], v[82:83] op_sel_hi:[1,0]
	v_pk_mul_f32 v[88:89], v[64:65], v[82:83] op_sel_hi:[1,0]
	v_pk_mul_f32 v[82:83], v[66:67], v[82:83] op_sel_hi:[1,0]
	v_pk_mul_f32 v[66:67], v[14:15], v[78:79]
	v_pk_mul_f32 v[64:65], v[12:13], v[76:77]
	v_pk_mul_f32 v[70:71], v[6:7], v[74:75]
	v_pk_mul_f32 v[68:69], v[4:5], v[72:73]
	v_pk_mul_f32 v[74:75], v[10:11], v[86:87]
	v_pk_mul_f32 v[72:73], v[8:9], v[84:85]
	v_pk_mul_f32 v[78:79], v[2:3], v[82:83]
	v_pk_mul_f32 v[76:77], v[0:1], v[88:89]
	global_store_dwordx4 v[80:81], v[64:67], off
	global_store_dwordx4 v[80:81], v[68:71], off offset:16
	global_store_dwordx4 v[80:81], v[72:75], off offset:512
	global_store_dwordx4 v[80:81], v[76:79], off offset:528
	global_load_dword v64, v[112:113], off offset:512 sc1
	s_waitcnt vmcnt(0)
	v_fmamk_f32 v64, v64, 0x3a000000, v160
	v_mul_f32_e32 v65, 0x4b800000, v64
	v_cmp_gt_f32_e32 vcc, s2, v64
	s_nop 1
	v_cndmask_b32_e32 v64, v64, v65, vcc
	v_rsq_f32_e32 v66, v64
	v_lshl_add_u64 v[64:65], v[164:165], 2, s[50:51]
	v_lshl_add_u64 v[64:65], v[64:65], 0, v[130:131]
	v_mul_f32_e32 v67, 0x45800000, v66
	v_cndmask_b32_e32 v66, v66, v67, vcc
	v_pk_mul_f32 v[60:61], v[60:61], v[66:67] op_sel_hi:[1,0]
	v_pk_mul_f32 v[62:63], v[62:63], v[66:67] op_sel_hi:[1,0]
	v_pk_mul_f32 v[56:57], v[56:57], v[66:67] op_sel_hi:[1,0]
	v_pk_mul_f32 v[58:59], v[58:59], v[66:67] op_sel_hi:[1,0]
	v_pk_mul_f32 v[68:69], v[52:53], v[66:67] op_sel_hi:[1,0]
	v_pk_mul_f32 v[70:71], v[54:55], v[66:67] op_sel_hi:[1,0]
	v_pk_mul_f32 v[72:73], v[48:49], v[66:67] op_sel_hi:[1,0]
	v_pk_mul_f32 v[66:67], v[50:51], v[66:67] op_sel_hi:[1,0]
	v_pk_mul_f32 v[50:51], v[14:15], v[62:63]
	v_pk_mul_f32 v[48:49], v[12:13], v[60:61]
	v_pk_mul_f32 v[54:55], v[6:7], v[58:59]
	v_pk_mul_f32 v[52:53], v[4:5], v[56:57]
	v_pk_mul_f32 v[58:59], v[10:11], v[70:71]
	v_pk_mul_f32 v[56:57], v[8:9], v[68:69]
	v_pk_mul_f32 v[62:63], v[2:3], v[66:67]
	v_pk_mul_f32 v[60:61], v[0:1], v[72:73]
	global_store_dwordx4 v[64:65], v[48:51], off
	global_store_dwordx4 v[64:65], v[52:55], off offset:16
	global_store_dwordx4 v[64:65], v[56:59], off offset:512
	global_store_dwordx4 v[64:65], v[60:63], off offset:528
	global_load_dword v48, v[112:113], off offset:576 sc1
	s_waitcnt vmcnt(0)
	v_fmamk_f32 v48, v48, 0x3a000000, v160
	v_mul_f32_e32 v49, 0x4b800000, v48
	v_cmp_gt_f32_e32 vcc, s2, v48
	s_nop 1
	v_cndmask_b32_e32 v48, v48, v49, vcc
	v_rsq_f32_e32 v50, v48
	v_lshl_add_u64 v[48:49], v[158:159], 2, s[50:51]
	v_lshl_add_u64 v[48:49], v[48:49], 0, v[130:131]
	v_mul_f32_e32 v51, 0x45800000, v50
	v_cndmask_b32_e32 v50, v50, v51, vcc
	v_pk_mul_f32 v[44:45], v[44:45], v[50:51] op_sel_hi:[1,0]
	v_pk_mul_f32 v[46:47], v[46:47], v[50:51] op_sel_hi:[1,0]
	v_pk_mul_f32 v[40:41], v[40:41], v[50:51] op_sel_hi:[1,0]
	v_pk_mul_f32 v[42:43], v[42:43], v[50:51] op_sel_hi:[1,0]
	v_pk_mul_f32 v[52:53], v[36:37], v[50:51] op_sel_hi:[1,0]
	v_pk_mul_f32 v[54:55], v[38:39], v[50:51] op_sel_hi:[1,0]
	v_pk_mul_f32 v[56:57], v[32:33], v[50:51] op_sel_hi:[1,0]
	v_pk_mul_f32 v[50:51], v[34:35], v[50:51] op_sel_hi:[1,0]
	v_pk_mul_f32 v[34:35], v[14:15], v[46:47]
	v_pk_mul_f32 v[32:33], v[12:13], v[44:45]
	v_pk_mul_f32 v[38:39], v[6:7], v[42:43]
	v_pk_mul_f32 v[36:37], v[4:5], v[40:41]
	v_pk_mul_f32 v[42:43], v[10:11], v[54:55]
	v_pk_mul_f32 v[40:41], v[8:9], v[52:53]
	v_pk_mul_f32 v[46:47], v[2:3], v[50:51]
	v_pk_mul_f32 v[44:45], v[0:1], v[56:57]
	global_store_dwordx4 v[48:49], v[32:35], off
	global_store_dwordx4 v[48:49], v[36:39], off offset:16
	global_store_dwordx4 v[48:49], v[40:43], off offset:512
	global_store_dwordx4 v[48:49], v[44:47], off offset:528
	global_load_dword v32, v[112:113], off offset:640 sc1
	s_waitcnt vmcnt(0)
	v_fmamk_f32 v32, v32, 0x3a000000, v160
	v_mul_f32_e32 v33, 0x4b800000, v32
	v_cmp_gt_f32_e32 vcc, s2, v32
	s_nop 1
	v_cndmask_b32_e32 v32, v32, v33, vcc
	v_rsq_f32_e32 v34, v32
	v_lshl_add_u64 v[32:33], v[156:157], 2, s[50:51]
	v_lshl_add_u64 v[32:33], v[32:33], 0, v[130:131]
	v_mul_f32_e32 v35, 0x45800000, v34
	v_cndmask_b32_e32 v34, v34, v35, vcc
	v_pk_mul_f32 v[28:29], v[28:29], v[34:35] op_sel_hi:[1,0]
	v_pk_mul_f32 v[30:31], v[30:31], v[34:35] op_sel_hi:[1,0]
	v_pk_mul_f32 v[24:25], v[24:25], v[34:35] op_sel_hi:[1,0]
	v_pk_mul_f32 v[26:27], v[26:27], v[34:35] op_sel_hi:[1,0]
	v_pk_mul_f32 v[36:37], v[20:21], v[34:35] op_sel_hi:[1,0]
	v_pk_mul_f32 v[38:39], v[22:23], v[34:35] op_sel_hi:[1,0]
	v_pk_mul_f32 v[40:41], v[16:17], v[34:35] op_sel_hi:[1,0]
	v_pk_mul_f32 v[34:35], v[18:19], v[34:35] op_sel_hi:[1,0]
	v_pk_mul_f32 v[18:19], v[14:15], v[30:31]
	v_pk_mul_f32 v[16:17], v[12:13], v[28:29]
	v_pk_mul_f32 v[22:23], v[6:7], v[26:27]
	v_pk_mul_f32 v[20:21], v[4:5], v[24:25]
	v_pk_mul_f32 v[26:27], v[10:11], v[38:39]
	v_pk_mul_f32 v[24:25], v[8:9], v[36:37]
	v_pk_mul_f32 v[30:31], v[2:3], v[34:35]
	v_pk_mul_f32 v[28:29], v[0:1], v[40:41]
	global_store_dwordx4 v[32:33], v[16:19], off
	global_store_dwordx4 v[32:33], v[20:23], off offset:16
	global_store_dwordx4 v[32:33], v[24:27], off offset:512
	global_store_dwordx4 v[32:33], v[28:31], off offset:528
	global_load_dword v16, v[112:113], off offset:704 sc1
	s_waitcnt vmcnt(0)
	v_fmac_f32_e32 v160, 0x3a000000, v16
	v_mul_f32_e32 v16, 0x4b800000, v160
	v_cmp_gt_f32_e32 vcc, s2, v160
	s_nop 1
	v_cndmask_b32_e32 v16, v160, v16, vcc
	v_rsq_f32_e32 v18, v16
	v_lshl_add_u64 v[16:17], v[134:135], 2, s[50:51]
	v_lshl_add_u64 v[16:17], v[16:17], 0, v[130:131]
	v_mul_f32_e32 v19, 0x45800000, v18
	v_cndmask_b32_e32 v18, v18, v19, vcc
	v_pk_mul_f32 v[20:21], v[154:155], v[18:19] op_sel_hi:[1,0]
	v_pk_mul_f32 v[22:23], v[152:153], v[18:19] op_sel_hi:[1,0]
	v_pk_mul_f32 v[24:25], v[150:151], v[18:19] op_sel_hi:[1,0]
	v_pk_mul_f32 v[26:27], v[148:149], v[18:19] op_sel_hi:[1,0]
	v_pk_mul_f32 v[28:29], v[146:147], v[18:19] op_sel_hi:[1,0]
	v_pk_mul_f32 v[30:31], v[144:145], v[18:19] op_sel_hi:[1,0]
	v_pk_mul_f32 v[32:33], v[142:143], v[18:19] op_sel_hi:[1,0]
	v_pk_mul_f32 v[18:19], v[140:141], v[18:19] op_sel_hi:[1,0]
	v_pk_mul_f32 v[14:15], v[14:15], v[22:23]
	v_pk_mul_f32 v[12:13], v[12:13], v[20:21]
	v_pk_mul_f32 v[6:7], v[6:7], v[26:27]
	v_pk_mul_f32 v[4:5], v[4:5], v[24:25]
	v_pk_mul_f32 v[10:11], v[10:11], v[30:31]
	v_pk_mul_f32 v[8:9], v[8:9], v[28:29]
	v_pk_mul_f32 v[2:3], v[2:3], v[18:19]
	v_pk_mul_f32 v[0:1], v[0:1], v[32:33]
	global_store_dwordx4 v[16:17], v[12:15], off
	global_store_dwordx4 v[16:17], v[4:7], off offset:16
	global_store_dwordx4 v[16:17], v[8:11], off offset:512
	global_store_dwordx4 v[16:17], v[0:3], off offset:528
	s_cmp_lg_u32 s2, 0
	s_cbranch_scc1 .Lflag_clr_done1
	v_readlane_b32 s4, v240, 9
	v_readlane_b32 s5, v240, 10
	v_readlane_b32 s6, v240, 35
	v_readlane_b32 s7, v240, 36
	s_and_b64 exec, exec, s[4:5]
	s_cbranch_execz .Lflag_clr_done1
	v_mov_b32_e32 v1, 0
	v_mov_b32_e32 v2, 0x3800
	s_nop 4
	global_store_dword v2, v1, s[6:7] sc0 sc1

	.amdhsa_kernel _Z8fwd_mega4Args
		.amdhsa_group_segment_fixed_size 0
		.amdhsa_private_segment_fixed_size 0
		.amdhsa_kernarg_size 512
		.amdhsa_user_sgpr_count 2
		.amdhsa_user_sgpr_dispatch_ptr 0
		.amdhsa_user_sgpr_queue_ptr 0
		.amdhsa_user_sgpr_kernarg_segment_ptr 1
		.amdhsa_user_sgpr_dispatch_id 0
		.amdhsa_user_sgpr_kernarg_preload_length 0
		.amdhsa_user_sgpr_kernarg_preload_offset 0
		.amdhsa_user_sgpr_private_segment_size 0
		.amdhsa_uses_dynamic_stack 0
		.amdhsa_enable_private_segment 0
		.amdhsa_system_sgpr_workgroup_id_x 1
		.amdhsa_system_sgpr_workgroup_id_y 0
		.amdhsa_system_sgpr_workgroup_id_z 0
		.amdhsa_system_sgpr_workgroup_info 0
		.amdhsa_system_vgpr_workitem_id 2
		.amdhsa_next_free_vgpr 256
		.amdhsa_next_free_sgpr 102
		.amdhsa_accum_offset 256
		.amdhsa_reserve_vcc 1
		.amdhsa_float_round_mode_32 0
		.amdhsa_float_round_mode_16_64 0
		.amdhsa_float_denorm_mode_32 3
		.amdhsa_float_denorm_mode_16_64 3
		.amdhsa_dx10_clamp 1
		.amdhsa_ieee_mode 1
		.amdhsa_fp16_overflow 0
		.amdhsa_tg_split 0
		.amdhsa_exception_fp_ieee_invalid_op 0
		.amdhsa_exception_fp_denorm_src 0
		.amdhsa_exception_fp_ieee_div_zero 0
		.amdhsa_exception_fp_ieee_overflow 0
		.amdhsa_exception_fp_ieee_underflow 0
		.amdhsa_exception_fp_ieee_inexact 0
		.amdhsa_exception_int_div_zero 0
	.end_amdhsa_kernel

amdhsa.kernels:
  - .agpr_count:     0
    .args:
      - .offset:         0
        .size:           256
        .value_kind:     by_value
      - .offset:         256
        .size:           4
        .value_kind:     hidden_block_count_x
      - .offset:         260
        .size:           4
        .value_kind:     hidden_block_count_y
      - .offset:         264
        .size:           4
        .value_kind:     hidden_block_count_z
      - .offset:         268
        .size:           2
        .value_kind:     hidden_group_size_x
      - .offset:         270
        .size:           2
        .value_kind:     hidden_group_size_y
      - .offset:         272
        .size:           2
        .value_kind:     hidden_group_size_z
      - .offset:         274
        .size:           2
        .value_kind:     hidden_remainder_x
      - .offset:         276
        .size:           2
        .value_kind:     hidden_remainder_y
      - .offset:         278
        .size:           2
        .value_kind:     hidden_remainder_z
      - .offset:         296
        .size:           8
        .value_kind:     hidden_global_offset_x
      - .offset:         304
        .size:           8
        .value_kind:     hidden_global_offset_y
      - .offset:         312
        .size:           8
        .value_kind:     hidden_global_offset_z
      - .offset:         320
        .size:           2
        .value_kind:     hidden_grid_dims
      - .offset:         344
        .size:           8
        .value_kind:     hidden_multigrid_sync_arg
      - .offset:         376
        .size:           4
        .value_kind:     hidden_dynamic_lds_size
    .group_segment_fixed_size: 0
    .kernarg_segment_align: 8
    .kernarg_segment_size: 512
    .language:       OpenCL C
    .language_version:
      - 2
      - 0
    .max_flat_workgroup_size: 512
    .name:           _Z8fwd_mega4Args
    .private_segment_fixed_size: 0
    .sgpr_count:     108
    .sgpr_spill_count: 37
    .symbol:         _Z8fwd_mega4Args.kd
    .uniform_work_group_size: 1
    .uses_dynamic_stack: false
    .vgpr_count:     256
    .vgpr_spill_count: 0
    .wavefront_size: 64
